# v23: prologue: the guarded (Klim=160) weight-transposition path issues its 8 row loads per step together instead of one round trip each (4 straggler CUs)
# speedup vs baseline: 1.0049x; 1.0049x over previous
; __device__ __forceinline__ void tr_item(const float* W, int N, int Klim, int k0, int n0, bf16* WT, int ldk, int drow, int dcol, const float* sc, float* scr, int lane, const float* sc2 = nullptr, bool nts = true) {
;     ...
;     } else {
; #pragma unroll 8
;         for (int i = 0; i < 32; ++i) { const int kk = 2 * i + (lane >> 5); const int k = k0 + kk; float v = 0.f; if (k < Klim) v = W[(size_t)k * N + n0 + (lane & 31)]; scr[kk * 33 + (lane & 31)] = v; }
;     }
.LBB0_774:
	s_movk_i32 s2, 0xa0
	v_mov_b32_e32 v112, 0
	v_cmp_gt_i32_e32 vcc, s2, v2
	s_and_saveexec_b64 s[52:53], vcc
	v_lshl_add_u64 v[50:51], v[46:47], 0, s[12:13]
	global_load_dword v112, v[50:51], off
	s_or_b64 exec, exec, s[52:53]
	v_mov_b32_e32 v113, 0
	v_add_u32_e32 v49, 2, v2
	v_cmp_gt_i32_e32 vcc, s2, v49
	s_and_saveexec_b64 s[52:53], vcc
	v_lshl_add_u64 v[50:51], v[44:45], 0, s[12:13]
	global_load_dword v113, v[50:51], off
	s_or_b64 exec, exec, s[52:53]
	v_mov_b32_e32 v114, 0
	v_add_u32_e32 v49, 4, v2
	v_cmp_gt_i32_e32 vcc, s2, v49
	s_and_saveexec_b64 s[52:53], vcc
	v_lshl_add_u64 v[50:51], v[42:43], 0, s[12:13]
	global_load_dword v114, v[50:51], off
	s_or_b64 exec, exec, s[52:53]
	v_mov_b32_e32 v115, 0
	v_add_u32_e32 v49, 6, v2
	v_cmp_gt_i32_e32 vcc, s2, v49
	s_and_saveexec_b64 s[52:53], vcc
	v_lshl_add_u64 v[50:51], v[40:41], 0, s[12:13]
	global_load_dword v115, v[50:51], off
	s_or_b64 exec, exec, s[52:53]
	v_mov_b32_e32 v116, 0
	v_add_u32_e32 v49, 8, v2
	v_cmp_gt_i32_e32 vcc, s2, v49
	s_and_saveexec_b64 s[52:53], vcc
	v_lshl_add_u64 v[50:51], v[38:39], 0, s[12:13]
	global_load_dword v116, v[50:51], off
	s_or_b64 exec, exec, s[52:53]
	v_mov_b32_e32 v117, 0
	v_add_u32_e32 v49, 10, v2
	v_cmp_gt_i32_e32 vcc, s2, v49
	s_and_saveexec_b64 s[52:53], vcc
	v_lshl_add_u64 v[50:51], v[8:9], 0, s[12:13]
	global_load_dword v117, v[50:51], off
	s_or_b64 exec, exec, s[52:53]
	v_mov_b32_e32 v118, 0
	v_add_u32_e32 v49, 12, v2
	v_cmp_gt_i32_e32 vcc, s2, v49
	s_and_saveexec_b64 s[52:53], vcc
	v_lshl_add_u64 v[50:51], v[6:7], 0, s[12:13]
	global_load_dword v118, v[50:51], off
	s_or_b64 exec, exec, s[52:53]
	v_mov_b32_e32 v119, 0
	v_add_u32_e32 v49, 14, v2
	v_cmp_gt_i32_e32 vcc, s2, v49
	s_and_saveexec_b64 s[52:53], vcc
	v_lshl_add_u64 v[50:51], v[4:5], 0, s[12:13]
	global_load_dword v119, v[50:51], off
	s_or_b64 exec, exec, s[52:53]
	s_waitcnt vmcnt(0)
	ds_write_b32 v3, v112
	ds_write_b32 v3, v113 offset:264
	ds_write_b32 v3, v114 offset:528
	ds_write_b32 v3, v115 offset:792
	ds_write_b32 v3, v116 offset:1056
	ds_write_b32 v3, v117 offset:1320
	ds_write_b32 v3, v118 offset:1584
	ds_write_b32 v3, v119 offset:1848
	s_add_u32 s12, s12, 0x10000
	s_addc_u32 s13, s13, 0
	v_add_u32_e32 v3, 0x840, v3
	v_add_u32_e32 v2, 16, v2
	s_cmp_eq_u32 s12, 0x40000
	s_cbranch_scc0 .LBB0_774
